# prep transpose loops: prefetch depth 2 (3 register sets), per-wave-group counted vmcnt
# baseline (speedup 1.0000x reference)
.LBB0_742:
	v_readlane_b32 s78, v253, 43
	s_mov_b32 s75, 0
	s_and_b32 s0, s51, 0x3c0
	s_and_b32 s46, s50, 0xffffffe0
	v_add_u32_e32 v110, s0, v11
	v_mov_b64_e32 v[108:109], s[40:41]
	s_movk_i32 s47, 0x6e80
	v_mad_i64_i32 v[108:109], s[48:49], v110, s47, v[108:109]
	s_ashr_i32 s47, s46, 31
	v_lshl_add_u64 v[108:109], s[46:47], 2, v[108:109]
	v_lshl_add_u64 v[108:109], v[108:109], 0, v[0:1]
	global_load_dwordx4 v[100:103], v[108:109], off
	v_readlane_b32 s71, v253, 7
	v_readlane_b32 s72, v253, 50
	v_readlane_b32 s70, v253, 20
	s_add_i32 s71, s51, s71
	s_add_i32 s72, s52, s72
	s_add_i32 s70, s50, s70
	s_cmpk_gt_i32 s72, 0xdcf
	s_cselect_b32 s73, 0, 1
	s_cbranch_scc1 .Lpg0_742_top0
	s_and_b32 s64, s71, 0x3c0
	s_and_b32 s66, s70, 0xffffffe0
	v_add_u32_e32 v110, s64, v11
	v_mov_b64_e32 v[108:109], s[40:41]
	s_movk_i32 s67, 0x6e80
	v_mad_i64_i32 v[108:109], s[68:69], v110, s67, v[108:109]
	s_ashr_i32 s67, s66, 31
	v_lshl_add_u64 v[108:109], s[66:67], 2, v[108:109]
	v_lshl_add_u64 v[108:109], v[108:109], 0, v[0:1]
	global_load_dwordx4 v[104:107], v[108:109], off
.Lpg0_742_top0:
	s_and_b32 s0, s51, 0x3c0
	s_and_b32 s46, s50, 0xffffffe0
	s_movk_i32 s47, 0x6e80
	s_ashr_i32 s47, s46, 31
	v_readlane_b32 s71, v253, 7
	v_readlane_b32 s72, v253, 50
	v_readlane_b32 s70, v253, 20
	s_lshl_b32 s71, s71, 1
	s_add_i32 s71, s51, s71
	s_lshl_b32 s72, s72, 1
	s_add_i32 s72, s52, s72
	s_lshl_b32 s70, s70, 1
	s_add_i32 s70, s50, s70
	s_cmpk_gt_i32 s72, 0xdcf
	s_cselect_b32 s74, 0, 1
	s_cbranch_scc1 .Lpg0_742_nopf0
	s_and_b32 s64, s71, 0x3c0
	s_and_b32 s66, s70, 0xffffffe0
	v_add_u32_e32 v110, s64, v11
	v_mov_b64_e32 v[108:109], s[40:41]
	s_movk_i32 s67, 0x6e80
	v_mad_i64_i32 v[108:109], s[68:69], v110, s67, v[108:109]
	s_ashr_i32 s67, s66, 31
	v_lshl_add_u64 v[108:109], s[66:67], 2, v[108:109]
	v_lshl_add_u64 v[108:109], v[108:109], 0, v[0:1]
	global_load_dwordx4 v[112:115], v[108:109], off
.Lpg0_742_nopf0:
	s_add_i32 s76, s73, s74
	s_cmpk_lt_u32 s78, 0x100
	s_cselect_b32 s77, 1, 0
	s_cmp_ge_u32 s75, 2
	s_cselect_b32 s77, s77, 0
	s_cmp_eq_u32 s77, 0
	s_cbranch_scc1 .Lpg0_742_ws0
	s_cmp_eq_u32 s76, 2
	s_cbranch_scc1 .Lpg0_742_wb20
	s_cmp_eq_u32 s76, 1
	s_cbranch_scc1 .Lpg0_742_wb10
	s_waitcnt vmcnt(2)
	s_branch .Lpg0_742_go0
.Lpg0_742_wb20:
	s_waitcnt vmcnt(4)
	s_branch .Lpg0_742_go0
.Lpg0_742_wb10:
	s_waitcnt vmcnt(3)
	s_branch .Lpg0_742_go0
.Lpg0_742_ws0:
	s_cmp_eq_u32 s76, 2
	s_cbranch_scc1 .Lpg0_742_ws20
	s_cmp_eq_u32 s76, 1
	s_cbranch_scc1 .Lpg0_742_ws10
	s_waitcnt vmcnt(0)
	s_branch .Lpg0_742_go0
.Lpg0_742_ws20:
	s_waitcnt vmcnt(2)
	s_branch .Lpg0_742_go0
.Lpg0_742_ws10:
	s_waitcnt vmcnt(1)
	s_branch .Lpg0_742_go0

.Lpg0_742_latch0:
	s_or_b64 exec, exec, s[48:49]
	v_readlane_b32 s71, v253, 7
	v_readlane_b32 s72, v253, 50
	v_readlane_b32 s70, v253, 20
	s_add_i32 s51, s51, s71
	s_add_i32 s52, s52, s72
	s_add_i32 s50, s50, s70
	s_mov_b32 s73, s74
	s_add_i32 s75, s75, 1
	s_min_u32 s75, s75, 2
	s_cmpk_gt_i32 s52, 0xdcf
	s_barrier
	v_readlane_b32 s47, v253, 51
	s_cbranch_scc1 .LBB0_744
.Lpg0_742_top1:
	s_and_b32 s0, s51, 0x3c0
	s_and_b32 s46, s50, 0xffffffe0
	s_movk_i32 s47, 0x6e80
	s_ashr_i32 s47, s46, 31
	v_readlane_b32 s71, v253, 7
	v_readlane_b32 s72, v253, 50
	v_readlane_b32 s70, v253, 20
	s_lshl_b32 s71, s71, 1
	s_add_i32 s71, s51, s71
	s_lshl_b32 s72, s72, 1
	s_add_i32 s72, s52, s72
	s_lshl_b32 s70, s70, 1
	s_add_i32 s70, s50, s70
	s_cmpk_gt_i32 s72, 0xdcf
	s_cselect_b32 s74, 0, 1
	s_cbranch_scc1 .Lpg0_742_nopf1
	s_and_b32 s64, s71, 0x3c0
	s_and_b32 s66, s70, 0xffffffe0
	v_add_u32_e32 v110, s64, v11
	v_mov_b64_e32 v[108:109], s[40:41]
	s_movk_i32 s67, 0x6e80
	v_mad_i64_i32 v[108:109], s[68:69], v110, s67, v[108:109]
	s_ashr_i32 s67, s66, 31
	v_lshl_add_u64 v[108:109], s[66:67], 2, v[108:109]
	v_lshl_add_u64 v[108:109], v[108:109], 0, v[0:1]
	global_load_dwordx4 v[100:103], v[108:109], off

.Lpg0_742_top2:
	s_and_b32 s0, s51, 0x3c0
	s_and_b32 s46, s50, 0xffffffe0
	s_movk_i32 s47, 0x6e80
	s_ashr_i32 s47, s46, 31
	v_readlane_b32 s71, v253, 7
	v_readlane_b32 s72, v253, 50
	v_readlane_b32 s70, v253, 20
	s_lshl_b32 s71, s71, 1
	s_add_i32 s71, s51, s71
	s_lshl_b32 s72, s72, 1
	s_add_i32 s72, s52, s72
	s_lshl_b32 s70, s70, 1
	s_add_i32 s70, s50, s70
	s_cmpk_gt_i32 s72, 0xdcf
	s_cselect_b32 s74, 0, 1
	s_cbranch_scc1 .Lpg0_742_nopf2
	s_and_b32 s64, s71, 0x3c0
	s_and_b32 s66, s70, 0xffffffe0
	v_add_u32_e32 v110, s64, v11
	v_mov_b64_e32 v[108:109], s[40:41]
	s_movk_i32 s67, 0x6e80
	v_mad_i64_i32 v[108:109], s[68:69], v110, s67, v[108:109]
	s_ashr_i32 s67, s66, 31
	v_lshl_add_u64 v[108:109], s[66:67], 2, v[108:109]
	v_lshl_add_u64 v[108:109], v[108:109], 0, v[0:1]
	global_load_dwordx4 v[104:107], v[108:109], off

.Lpg0_742_go2:
	v_cvt_pk_bf16_f32 v2, v112, s0
	v_cvt_pk_bf16_f32 v3, v113, s0
	v_cvt_pk_bf16_f32 v4, v114, s0
	v_cvt_pk_bf16_f32 v5, v115, s0
	ds_write_b16 v12, v2
	ds_write_b16 v12, v3 offset:144
	ds_write_b16 v12, v4 offset:288
	ds_write_b16 v12, v5 offset:432
	s_waitcnt lgkmcnt(0)
	s_barrier
	s_and_saveexec_b64 s[48:49], s[4:5]
	s_cbranch_execz .Lpg0_742_latch2
	s_add_i32 s47, s46, 0x60
	s_cmpk_lt_i32 s46, 0x1a0
	s_cselect_b32 s46, s46, s47
	v_add_u32_e32 v6, s46, v11
	ds_read_b128 v[2:5], v14
	v_ashrrev_i32_e32 v7, 31, v6
	v_lshlrev_b64 v[6:7], 11, v[6:7]
	v_lshl_add_u64 v[6:7], s[44:45], 0, v[6:7]
	s_lshl_b32 s0, s0, 1
	v_lshl_add_u64 v[6:7], v[6:7], 0, s[0:1]
	v_lshlrev_b32_e32 v8, 1, v13
	v_mov_b32_e32 v9, v1
	v_lshl_add_u64 v[6:7], v[6:7], 0, v[8:9]
	s_waitcnt lgkmcnt(0)
	global_store_dwordx4 v[6:7], v[2:5], off
.Lpg0_742_latch2:
	s_or_b64 exec, exec, s[48:49]
	v_readlane_b32 s71, v253, 7
	v_readlane_b32 s72, v253, 50
	v_readlane_b32 s70, v253, 20
	s_add_i32 s51, s51, s71
	s_add_i32 s52, s52, s72
	s_add_i32 s50, s50, s70
	s_mov_b32 s73, s74
	s_add_i32 s75, s75, 1
	s_min_u32 s75, s75, 2
	s_cmpk_gt_i32 s52, 0xdcf
	s_barrier
	v_readlane_b32 s47, v253, 51
	s_cbranch_scc1 .LBB0_744
	s_branch .Lpg0_742_top0

.LBB0_768:
	v_readlane_b32 s78, v253, 43
	s_mov_b32 s75, 0
	s_ashr_i32 s6, s49, 7
	s_ashr_i32 s7, s6, 31
	s_and_b32 s50, s49, 0x60
	s_lshl_b64 s[24:25], s[6:7], 20
	s_add_u32 s24, s46, s24
	s_addc_u32 s25, s47, s25
	s_and_b32 s7, s48, 0x7c0
	v_add_u32_e32 v108, s7, v11
	v_ashrrev_i32_e32 v109, 31, v108
	v_lshlrev_b64 v[108:109], 9, v[108:109]
	v_lshl_add_u64 v[108:109], s[24:25], 0, v[108:109]
	s_lshl_b32 s0, s50, 2
	v_lshl_add_u64 v[108:109], v[108:109], 0, s[0:1]
	v_lshl_add_u64 v[108:109], v[108:109], 0, v[0:1]
	global_load_dwordx4 v[100:103], v[108:109], off
	v_readlane_b32 s71, v253, 50
	v_readlane_b32 s70, v253, 7
	s_add_i32 s71, s49, s71
	s_add_i32 s70, s48, s70
	s_cmpk_gt_i32 s71, 0x3ff
	s_cselect_b32 s73, 0, 1
	s_cbranch_scc1 .Lpg2_768_top0
	s_mov_b32 s65, s1
	s_ashr_i32 s66, s71, 7
	s_ashr_i32 s67, s66, 31
	s_and_b32 s72, s71, 0x60
	s_lshl_b64 s[68:69], s[66:67], 20
	s_add_u32 s68, s46, s68
	s_addc_u32 s69, s47, s69
	s_and_b32 s67, s70, 0x7c0
	v_add_u32_e32 v108, s67, v11
	v_ashrrev_i32_e32 v109, 31, v108
	v_lshlrev_b64 v[108:109], 9, v[108:109]
	v_lshl_add_u64 v[108:109], s[68:69], 0, v[108:109]
	s_lshl_b32 s64, s72, 2
	v_lshl_add_u64 v[108:109], v[108:109], 0, s[64:65]
	v_lshl_add_u64 v[108:109], v[108:109], 0, v[0:1]
	global_load_dwordx4 v[104:107], v[108:109], off
.Lpg2_768_top0:
	s_ashr_i32 s6, s49, 7
	s_ashr_i32 s7, s6, 31
	s_and_b32 s50, s49, 0x60
	s_lshl_b64 s[24:25], s[6:7], 20
	s_add_u32 s24, s46, s24
	s_addc_u32 s25, s47, s25
	s_and_b32 s7, s48, 0x7c0
	s_lshl_b32 s0, s50, 2
	v_readlane_b32 s71, v253, 50
	v_readlane_b32 s70, v253, 7
	s_lshl_b32 s71, s71, 1
	s_add_i32 s71, s49, s71
	s_lshl_b32 s70, s70, 1
	s_add_i32 s70, s48, s70
	s_cmpk_gt_i32 s71, 0x3ff
	s_cselect_b32 s74, 0, 1
	s_cbranch_scc1 .Lpg2_768_nopf0
	s_mov_b32 s65, s1
	s_ashr_i32 s66, s71, 7
	s_ashr_i32 s67, s66, 31
	s_and_b32 s72, s71, 0x60
	s_lshl_b64 s[68:69], s[66:67], 20
	s_add_u32 s68, s46, s68
	s_addc_u32 s69, s47, s69
	s_and_b32 s67, s70, 0x7c0
	v_add_u32_e32 v108, s67, v11
	v_ashrrev_i32_e32 v109, 31, v108
	v_lshlrev_b64 v[108:109], 9, v[108:109]
	v_lshl_add_u64 v[108:109], s[68:69], 0, v[108:109]
	s_lshl_b32 s64, s72, 2
	v_lshl_add_u64 v[108:109], v[108:109], 0, s[64:65]
	v_lshl_add_u64 v[108:109], v[108:109], 0, v[0:1]
	global_load_dwordx4 v[112:115], v[108:109], off
.Lpg2_768_nopf0:
	s_add_i32 s76, s73, s74
	s_cmpk_lt_u32 s78, 0x100
	s_cselect_b32 s77, 1, 0
	s_cmp_ge_u32 s75, 2
	s_cselect_b32 s77, s77, 0
	s_cmp_eq_u32 s77, 0
	s_cbranch_scc1 .Lpg2_768_ws0
	s_cmp_eq_u32 s76, 2
	s_cbranch_scc1 .Lpg2_768_wb20
	s_cmp_eq_u32 s76, 1
	s_cbranch_scc1 .Lpg2_768_wb10
	s_waitcnt vmcnt(4)
	s_branch .Lpg2_768_go0
.Lpg2_768_wb20:
	s_waitcnt vmcnt(6)
	s_branch .Lpg2_768_go0
.Lpg2_768_wb10:
	s_waitcnt vmcnt(5)
	s_branch .Lpg2_768_go0

.Lpg2_768_latch0:
	s_or_b64 exec, exec, s[24:25]
	v_readlane_b32 s71, v253, 50
	v_readlane_b32 s70, v253, 7
	s_add_i32 s49, s49, s71
	s_add_i32 s48, s48, s70
	s_mov_b32 s73, s74
	s_add_i32 s75, s75, 1
	s_min_u32 s75, s75, 2
	s_cmpk_gt_i32 s49, 0x3ff
	s_barrier
	v_readlane_b32 s7, v253, 51
	s_cbranch_scc1 .LBB0_770
.Lpg2_768_top1:
	s_ashr_i32 s6, s49, 7
	s_ashr_i32 s7, s6, 31
	s_and_b32 s50, s49, 0x60
	s_lshl_b64 s[24:25], s[6:7], 20
	s_add_u32 s24, s46, s24
	s_addc_u32 s25, s47, s25
	s_and_b32 s7, s48, 0x7c0
	s_lshl_b32 s0, s50, 2
	v_readlane_b32 s71, v253, 50
	v_readlane_b32 s70, v253, 7
	s_lshl_b32 s71, s71, 1
	s_add_i32 s71, s49, s71
	s_lshl_b32 s70, s70, 1
	s_add_i32 s70, s48, s70
	s_cmpk_gt_i32 s71, 0x3ff
	s_cselect_b32 s74, 0, 1
	s_cbranch_scc1 .Lpg2_768_nopf1
	s_mov_b32 s65, s1
	s_ashr_i32 s66, s71, 7
	s_ashr_i32 s67, s66, 31
	s_and_b32 s72, s71, 0x60
	s_lshl_b64 s[68:69], s[66:67], 20
	s_add_u32 s68, s46, s68
	s_addc_u32 s69, s47, s69
	s_and_b32 s67, s70, 0x7c0
	v_add_u32_e32 v108, s67, v11
	v_ashrrev_i32_e32 v109, 31, v108
	v_lshlrev_b64 v[108:109], 9, v[108:109]
	v_lshl_add_u64 v[108:109], s[68:69], 0, v[108:109]
	s_lshl_b32 s64, s72, 2
	v_lshl_add_u64 v[108:109], v[108:109], 0, s[64:65]
	v_lshl_add_u64 v[108:109], v[108:109], 0, v[0:1]
	global_load_dwordx4 v[100:103], v[108:109], off

.Lpg2_768_top2:
	s_ashr_i32 s6, s49, 7
	s_ashr_i32 s7, s6, 31
	s_and_b32 s50, s49, 0x60
	s_lshl_b64 s[24:25], s[6:7], 20
	s_add_u32 s24, s46, s24
	s_addc_u32 s25, s47, s25
	s_and_b32 s7, s48, 0x7c0
	s_lshl_b32 s0, s50, 2
	v_readlane_b32 s71, v253, 50
	v_readlane_b32 s70, v253, 7
	s_lshl_b32 s71, s71, 1
	s_add_i32 s71, s49, s71
	s_lshl_b32 s70, s70, 1
	s_add_i32 s70, s48, s70
	s_cmpk_gt_i32 s71, 0x3ff
	s_cselect_b32 s74, 0, 1
	s_cbranch_scc1 .Lpg2_768_nopf2
	s_mov_b32 s65, s1
	s_ashr_i32 s66, s71, 7
	s_ashr_i32 s67, s66, 31
	s_and_b32 s72, s71, 0x60
	s_lshl_b64 s[68:69], s[66:67], 20
	s_add_u32 s68, s46, s68
	s_addc_u32 s69, s47, s69
	s_and_b32 s67, s70, 0x7c0
	v_add_u32_e32 v108, s67, v11
	v_ashrrev_i32_e32 v109, 31, v108
	v_lshlrev_b64 v[108:109], 9, v[108:109]
	v_lshl_add_u64 v[108:109], s[68:69], 0, v[108:109]
	s_lshl_b32 s64, s72, 2
	v_lshl_add_u64 v[108:109], v[108:109], 0, s[64:65]
	v_lshl_add_u64 v[108:109], v[108:109], 0, v[0:1]
	global_load_dwordx4 v[104:107], v[108:109], off

.Lpg2_768_go2:
	v_cvt_pk_bf16_f32 v4, v112, s0
	v_cvt_pk_bf16_f32 v5, v113, s0
	v_cvt_pk_bf16_f32 v6, v114, s0
	v_cvt_pk_bf16_f32 v7, v115, s0
	ds_write_b16 v12, v4
	ds_write_b16 v12, v5 offset:144
	ds_write_b16 v12, v6 offset:288
	ds_write_b16 v12, v7 offset:432
	s_waitcnt lgkmcnt(0)
	s_barrier
	s_and_saveexec_b64 s[24:25], s[4:5]
	s_cbranch_execz .Lpg2_768_latch2
	s_mul_hi_i32 s0, s6, 0x84000
	s_mul_i32 s6, s6, 0x84000
	s_add_u32 s52, s26, s6
	s_addc_u32 s53, s27, s0
	ds_read_b128 v[4:7], v14
	v_add_u32_e32 v10, s50, v11
	v_mov_b64_e32 v[8:9], s[52:53]
	s_movk_i32 s0, 0x1080
	v_mad_i64_i32 v[8:9], s[50:51], v10, s0, v[8:9]
	v_or_b32_e32 v10, s7, v13
	s_movk_i32 s0, 0x7f0
	v_and_or_b32 v15, v10, s0, v2
	v_lshlrev_b32_e32 v16, 1, v15
	v_mov_b32_e32 v17, v1
	v_lshl_add_u64 v[16:17], v[8:9], 0, v[16:17]
	s_waitcnt lgkmcnt(0)
	global_store_dwordx2 v[16:17], v[4:5], off
	v_or_b32_e32 v4, v10, v3
	v_lshlrev_b32_e32 v4, 1, v4
	v_mov_b32_e32 v5, v1
	v_lshl_add_u64 v[4:5], v[8:9], 0, v[4:5]
	global_store_dwordx2 v[4:5], v[6:7], off
.Lpg2_768_latch2:
	s_or_b64 exec, exec, s[24:25]
	v_readlane_b32 s71, v253, 50
	v_readlane_b32 s70, v253, 7
	s_add_i32 s49, s49, s71
	s_add_i32 s48, s48, s70
	s_mov_b32 s73, s74
	s_add_i32 s75, s75, 1
	s_min_u32 s75, s75, 2
	s_cmpk_gt_i32 s49, 0x3ff
	s_barrier
	v_readlane_b32 s7, v253, 51
	s_cbranch_scc1 .LBB0_770
	s_branch .Lpg2_768_top0

.LBB0_773:
	v_readlane_b32 s78, v253, 43
	s_mov_b32 s75, 0
	s_ashr_i32 s14, s51, 9
	s_ashr_i32 s15, s14, 31
	s_and_b32 s52, s51, 0x1e0
	s_lshl_b64 s[46:47], s[14:15], 22
	s_add_u32 s46, s48, s46
	s_addc_u32 s47, s49, s47
	s_and_b32 s15, s50, 0x7c0
	v_add_u32_e32 v108, s15, v11
	v_ashrrev_i32_e32 v109, 31, v108
	v_lshlrev_b64 v[108:109], 11, v[108:109]
	v_lshl_add_u64 v[108:109], s[46:47], 0, v[108:109]
	s_lshl_b32 s0, s52, 2
	v_lshl_add_u64 v[108:109], v[108:109], 0, s[0:1]
	v_lshl_add_u64 v[108:109], v[108:109], 0, v[0:1]
	global_load_dwordx4 v[100:103], v[108:109], off
	v_readlane_b32 s71, v253, 50
	v_readlane_b32 s70, v253, 7
	s_add_i32 s71, s51, s71
	s_add_i32 s70, s50, s70
	s_cmpk_gt_i32 s71, 0xfff
	s_cselect_b32 s73, 0, 1
	s_cbranch_scc1 .Lpg1_773_top0
	s_mov_b32 s65, s1
	s_ashr_i32 s66, s71, 9
	s_ashr_i32 s67, s66, 31
	s_and_b32 s72, s71, 0x1e0
	s_lshl_b64 s[68:69], s[66:67], 22
	s_add_u32 s68, s48, s68
	s_addc_u32 s69, s49, s69
	s_and_b32 s67, s70, 0x7c0
	v_add_u32_e32 v108, s67, v11
	v_ashrrev_i32_e32 v109, 31, v108
	v_lshlrev_b64 v[108:109], 11, v[108:109]
	v_lshl_add_u64 v[108:109], s[68:69], 0, v[108:109]
	s_lshl_b32 s64, s72, 2
	v_lshl_add_u64 v[108:109], v[108:109], 0, s[64:65]
	v_lshl_add_u64 v[108:109], v[108:109], 0, v[0:1]
	global_load_dwordx4 v[104:107], v[108:109], off
.Lpg1_773_top0:
	s_ashr_i32 s14, s51, 9
	s_ashr_i32 s15, s14, 31
	s_and_b32 s52, s51, 0x1e0
	s_lshl_b64 s[46:47], s[14:15], 22
	s_add_u32 s46, s48, s46
	s_addc_u32 s47, s49, s47
	s_and_b32 s15, s50, 0x7c0
	s_lshl_b32 s0, s52, 2
	v_readlane_b32 s71, v253, 50
	v_readlane_b32 s70, v253, 7
	s_lshl_b32 s71, s71, 1
	s_add_i32 s71, s51, s71
	s_lshl_b32 s70, s70, 1
	s_add_i32 s70, s50, s70
	s_cmpk_gt_i32 s71, 0xfff
	s_cselect_b32 s74, 0, 1
	s_cbranch_scc1 .Lpg1_773_nopf0
	s_mov_b32 s65, s1
	s_ashr_i32 s66, s71, 9
	s_ashr_i32 s67, s66, 31
	s_and_b32 s72, s71, 0x1e0
	s_lshl_b64 s[68:69], s[66:67], 22
	s_add_u32 s68, s48, s68
	s_addc_u32 s69, s49, s69
	s_and_b32 s67, s70, 0x7c0
	v_add_u32_e32 v108, s67, v11
	v_ashrrev_i32_e32 v109, 31, v108
	v_lshlrev_b64 v[108:109], 11, v[108:109]
	v_lshl_add_u64 v[108:109], s[68:69], 0, v[108:109]
	s_lshl_b32 s64, s72, 2
	v_lshl_add_u64 v[108:109], v[108:109], 0, s[64:65]
	v_lshl_add_u64 v[108:109], v[108:109], 0, v[0:1]
	global_load_dwordx4 v[112:115], v[108:109], off

.Lpg1_773_latch0:
	s_or_b64 exec, exec, s[46:47]
	v_readlane_b32 s71, v253, 50
	v_readlane_b32 s70, v253, 7
	s_add_i32 s51, s51, s71
	s_add_i32 s50, s50, s70
	s_mov_b32 s73, s74
	s_add_i32 s75, s75, 1
	s_min_u32 s75, s75, 2
	s_cmpk_gt_i32 s51, 0xfff
	s_barrier
	v_readlane_b32 s15, v253, 51
	s_cbranch_scc1 .LBB0_775
.Lpg1_773_top1:
	s_ashr_i32 s14, s51, 9
	s_ashr_i32 s15, s14, 31
	s_and_b32 s52, s51, 0x1e0
	s_lshl_b64 s[46:47], s[14:15], 22
	s_add_u32 s46, s48, s46
	s_addc_u32 s47, s49, s47
	s_and_b32 s15, s50, 0x7c0
	s_lshl_b32 s0, s52, 2
	v_readlane_b32 s71, v253, 50
	v_readlane_b32 s70, v253, 7
	s_lshl_b32 s71, s71, 1
	s_add_i32 s71, s51, s71
	s_lshl_b32 s70, s70, 1
	s_add_i32 s70, s50, s70
	s_cmpk_gt_i32 s71, 0xfff
	s_cselect_b32 s74, 0, 1
	s_cbranch_scc1 .Lpg1_773_nopf1
	s_mov_b32 s65, s1
	s_ashr_i32 s66, s71, 9
	s_ashr_i32 s67, s66, 31
	s_and_b32 s72, s71, 0x1e0
	s_lshl_b64 s[68:69], s[66:67], 22
	s_add_u32 s68, s48, s68
	s_addc_u32 s69, s49, s69
	s_and_b32 s67, s70, 0x7c0
	v_add_u32_e32 v108, s67, v11
	v_ashrrev_i32_e32 v109, 31, v108
	v_lshlrev_b64 v[108:109], 11, v[108:109]
	v_lshl_add_u64 v[108:109], s[68:69], 0, v[108:109]
	s_lshl_b32 s64, s72, 2
	v_lshl_add_u64 v[108:109], v[108:109], 0, s[64:65]
	v_lshl_add_u64 v[108:109], v[108:109], 0, v[0:1]
	global_load_dwordx4 v[100:103], v[108:109], off

.Lpg1_773_top2:
	s_ashr_i32 s14, s51, 9
	s_ashr_i32 s15, s14, 31
	s_and_b32 s52, s51, 0x1e0
	s_lshl_b64 s[46:47], s[14:15], 22
	s_add_u32 s46, s48, s46
	s_addc_u32 s47, s49, s47
	s_and_b32 s15, s50, 0x7c0
	s_lshl_b32 s0, s52, 2
	v_readlane_b32 s71, v253, 50
	v_readlane_b32 s70, v253, 7
	s_lshl_b32 s71, s71, 1
	s_add_i32 s71, s51, s71
	s_lshl_b32 s70, s70, 1
	s_add_i32 s70, s50, s70
	s_cmpk_gt_i32 s71, 0xfff
	s_cselect_b32 s74, 0, 1
	s_cbranch_scc1 .Lpg1_773_nopf2
	s_mov_b32 s65, s1
	s_ashr_i32 s66, s71, 9
	s_ashr_i32 s67, s66, 31
	s_and_b32 s72, s71, 0x1e0
	s_lshl_b64 s[68:69], s[66:67], 22
	s_add_u32 s68, s48, s68
	s_addc_u32 s69, s49, s69
	s_and_b32 s67, s70, 0x7c0
	v_add_u32_e32 v108, s67, v11
	v_ashrrev_i32_e32 v109, 31, v108
	v_lshlrev_b64 v[108:109], 11, v[108:109]
	v_lshl_add_u64 v[108:109], s[68:69], 0, v[108:109]
	s_lshl_b32 s64, s72, 2
	v_lshl_add_u64 v[108:109], v[108:109], 0, s[64:65]
	v_lshl_add_u64 v[108:109], v[108:109], 0, v[0:1]
	global_load_dwordx4 v[104:107], v[108:109], off

.Lpg1_773_go2:
	v_cvt_pk_bf16_f32 v4, v112, s0
	v_cvt_pk_bf16_f32 v5, v113, s0
	v_cvt_pk_bf16_f32 v6, v114, s0
	v_cvt_pk_bf16_f32 v7, v115, s0
	ds_write_b16 v12, v4
	ds_write_b16 v12, v5 offset:144
	ds_write_b16 v12, v6 offset:288
	ds_write_b16 v12, v7 offset:432
	s_waitcnt lgkmcnt(0)
	s_barrier
	s_and_saveexec_b64 s[46:47], s[4:5]
	s_cbranch_execz .Lpg1_773_latch2
	s_mul_hi_i32 s0, s14, 0x210000
	s_mul_i32 s14, s14, 0x210000
	s_add_u32 s54, s24, s14
	s_addc_u32 s55, s25, s0
	ds_read_b128 v[4:7], v14
	v_add_u32_e32 v10, s52, v11
	v_mov_b64_e32 v[8:9], s[54:55]
	s_movk_i32 s0, 0x1080
	v_mad_i64_i32 v[8:9], s[52:53], v10, s0, v[8:9]
	v_or_b32_e32 v10, s15, v13
	s_movk_i32 s0, 0x7f0
	v_and_or_b32 v15, v10, s0, v2
	v_lshlrev_b32_e32 v16, 1, v15
	v_mov_b32_e32 v17, v1
	v_lshl_add_u64 v[16:17], v[8:9], 0, v[16:17]
	s_waitcnt lgkmcnt(0)
	global_store_dwordx2 v[16:17], v[4:5], off
	v_or_b32_e32 v4, v10, v3
	v_lshlrev_b32_e32 v4, 1, v4
	v_mov_b32_e32 v5, v1
	v_lshl_add_u64 v[4:5], v[8:9], 0, v[4:5]
	global_store_dwordx2 v[4:5], v[6:7], off
.Lpg1_773_latch2:
	s_or_b64 exec, exec, s[46:47]
	v_readlane_b32 s71, v253, 50
	v_readlane_b32 s70, v253, 7
	s_add_i32 s51, s51, s71
	s_add_i32 s50, s50, s70
	s_mov_b32 s73, s74
	s_add_i32 s75, s75, 1
	s_min_u32 s75, s75, 2
	s_cmpk_gt_i32 s51, 0xfff
	s_barrier
	v_readlane_b32 s15, v253, 51
	s_cbranch_scc1 .LBB0_775
	s_branch .Lpg1_773_top0
